# variant: three workgroup groups with rotated P2 sub-phase orders (F,C,P / C,P,F / C,F,P)
# baseline (speedup 1.0000x reference)
; #define LAS __attribute__((address_space(3)))
; __global__ void __launch_bounds__(512, 2) fwd_megakernel(Params p_) {
;     ...
;         if (PHM & 8)
;         {
;             TID_VARS
;             KARGS
;             { LAS float* WD0 = (LAS float*)lds; const float* wdw = p->in[I_WDW] + (size_t)l * 31 * 512;
;               for (int e = tid; e < 31 * 512; e += 512) WD0[e] = wdw[e]; }
.LBB0_291:
	s_or_b64 exec, exec, s[38:39]
	v_readlane_b32 s0, v253, 0
	v_mov_b32_e32 v48, v246
	v_readlane_b32 s1, v253, 1
	s_waitcnt lgkmcnt(0)
	s_barrier
	v_readlane_b32 s101, v253, 7
	s_nop 0
	s_lshr_b32 s101, s101, 3
	s_mul_i32 s100, s101, 43
	s_lshr_b32 s100, s100, 7
	s_mul_i32 s100, s100, 3
	s_sub_u32 s101, s101, s100
	s_movk_i32 s2, 0x3e00
	v_writelane_b32 v255, s0, 10
	s_load_dwordx2 s[6:7], s[0:1], 0xd0
	v_ashrrev_i32_e32 v49, 31, v48
	v_writelane_b32 v255, s1, 11
	v_readfirstlane_b32 s0, v48
	v_cmp_gt_i32_e32 vcc, s2, v48
	s_nop 0
	v_writelane_b32 v255, s0, 12
	s_and_saveexec_b64 s[8:9], vcc
	s_cbranch_execz .LBB0_306
	v_readlane_b32 s0, v255, 10
	v_readlane_b32 s1, v255, 11
	s_load_dwordx2 s[10:11], s[0:1], 0x68
	v_max_i32_e32 v0, 0x3c00, v48
	v_sub_u32_e32 v0, v0, v48
	v_add_u32_e32 v1, 0x1ff, v0
	s_movk_i32 s2, 0x1ff
	v_cmp_lt_u32_e32 vcc, s2, v1
	s_mov_b64 s[4:5], -1
	v_mov_b32_e32 v0, v48
	v_mov_b64_e32 v[2:3], v[48:49]
	s_and_saveexec_b64 s[12:13], vcc
	s_cbranch_execz .LBB0_303
	v_lshrrev_b32_e32 v2, 9, v1
	v_readlane_b32 s0, v255, 6
	s_mul_i32 s3, s0, 0xf800
	v_add_u32_e32 v4, -1, v2
	s_mul_hi_u32 s2, s0, 0xf800
	s_waitcnt lgkmcnt(0)
	s_add_u32 s14, s10, s3
	v_lshrrev_b32_e32 v3, 1, v4
	s_addc_u32 s15, s11, s2
	v_add_u32_e32 v1, 0x200, v48
	v_mov_b32_e32 v0, v48
	v_add_u32_e32 v3, 1, v3
	v_cmp_lt_u32_e32 vcc, 13, v4
	v_mov_b32_e32 v6, 0
	v_readlane_b32 s1, v255, 7
	s_and_saveexec_b64 s[16:17], vcc
	s_cbranch_execz .LBB0_297
	v_and_b32_e32 v4, -8, v3
	v_lshl_add_u32 v5, v48, 2, 0
	s_mov_b32 s2, 0
	s_mov_b64 s[18:19], 0

; __global__ void __launch_bounds__(512, 2) fwd_megakernel(Params p_) {
;     ...
;             for (int t = bid; t < 1024; t += G) {
;                 int base, n1, S1, lS;
;                 if (t < 512) { base = (t >> 6) * 2048; n1 = t & 63; S1 = 64; lS = 11; } else { const int tt = t - 512; base = M_PROMPT + (tt >> 8) * 8192; n1 = tt & 255; S1 = 256; lS = 13; }
;                 __syncthreads();
;                 if (tid < 32) TW2[tid] = TWT[(t < 512 ? TW_2A : TW_2B) + n1 * 32 + tid];
.LBB0_306:
	s_or_b64 exec, exec, s[8:9]
	v_readlane_b32 s2, v253, 13
	v_readlane_b32 s3, v253, 14
	s_andn2_b64 vcc, exec, s[2:3]
	s_nop 0
	v_cndmask_b32_e64 v0, 0, 1, s[2:3]
	v_cmp_ne_u32_e64 s[0:1], 1, v0
	s_nop 1
	v_writelane_b32 v255, s0, 13
	s_nop 1
	v_writelane_b32 v255, s1, 14
	s_cbranch_vccnz .LBB0_316
	s_cmp_eq_u32 s101, 0
	s_cbranch_scc0 .LBB0_316

; __global__ void __launch_bounds__(512, 2) fwd_megakernel(Params p_) {
;     ...
;                     ZB[(size_t)(base + k2 * S1 + n1) * 512 + tid] = (f32x2){re[i2] * w.x - im[i2] * w.y, re[i2] * w.y + im[i2] * w.x}; } }
;             }
;             __syncthreads();
;             {
.LBB0_316:
	s_cmp_lt_u32 s101, 3
	s_cbranch_scc1 .Lp2_c316
	v_readlane_b32 s2, v253, 15
	v_readlane_b32 s3, v253, 16
	s_nop 1
	v_cndmask_b32_e64 v0, 0, 1, s[2:3]
	v_cmp_ne_u32_e64 s[8:9], 1, v0
	s_cmp_eq_u32 s101, 3
	s_cbranch_scc1 .LBB0_504
	v_add_u32_e32 v37, 0x200, v48
	v_add_u32_e32 v52, 0x400, v48
	v_add_u32_e32 v53, 0x600, v48
	v_add_u32_e32 v54, 0x800, v48
	v_add_u32_e32 v55, 0xa00, v48
	v_add_u32_e32 v56, 0xc00, v48
	v_add_u32_e32 v57, 0xe00, v48
	s_branch .LBB0_475

; __global__ void __launch_bounds__(512, 2) fwd_megakernel(Params p_) {
;     ...
;             {
;                 const float* bg = p->in[I_BG] + l * 1024; const float* psc = p->in[I_PSC] + l * 1024;
;                 for (int rb = bid; rb < M_TOK / 128; rb += G) {
.LBB0_475:
	s_cmp_eq_u32 s101, 2
	s_cbranch_scc0 .Lp2_cont475
	s_mov_b32 s101, 4
	s_branch .Lp2_fft1
